# attention: no VALU in the first two MFMA gaps of an iteration (bare-MFMA head behind the rotated barrier)
# speedup vs baseline: 1.0099x; 1.0099x over previous
; __device__ __forceinline__ float fast_exp2(float x) { return __builtin_amdgcn_exp2f(x); }
; #define LGK(n, f) asm volatile("s_waitcnt lgkmcnt(%1)" : "+v"(f) : "n"(n))
; #define ATT_KRD(i) DSR(fr_[(i) & 3], kad[((i) >> 1) & 3], ((i) & 1) * (32 * 384) + ((i) >> 3) * 128)
; __device__ __forceinline__ void attn_phase(int wv, const bf16_t* Q, const bf16_t* Kf, const bf16_t* Vt, const bf16_t* proj, bf16_t* mixed, LAS unsigned char* lds) { LIDS
;     ...
;                     for (int kb = 0; kb < 2; ++kb)
; #pragma unroll
;                         for (int j = 0; j < 16; ++j) s[kb][j] = zf;
;                     unsigned kad[4];
; #pragma unroll
;                     for (int kl = 0; kl < 4; ++kl) kad[kl] = (unsigned)(size_t)kb_ + (unsigned)koffl[kl];
;                     bf16x8 fr_[4];
;     ...
;                     ATT_KRD(0); ATT_KRD(1); ATT_KRD(2); ATT_KRD(3);
; #pragma unroll
;                     for (int i = 0; i < 24; ++i) {
;                         LGK(i < 21 ? 3 : 23 - i, fr_[i & 3]);
;                         s[i & 1] = __builtin_amdgcn_mfma_f32_32x32x16_bf16(fr_[i & 3], qf[i >> 1], s[i & 1], 0, 0, 0);
;                         if (i + 4 < 24) ATT_KRD(i + 4);
;                     }
;     ...
;                     float ps = 0.f;
; #pragma unroll
;                     for (int kb = 0; kb < 2; ++kb)
; #pragma unroll
;                         for (int j = 0; j < 16; ++j) { s[kb][j] = fast_exp2(s[kb][j] - mrun); ps += s[kb][j]; }
;                     lsum += ps;
.Lp2_top0:
	s_waitcnt lgkmcnt(3)
	v_mfma_f32_32x32x16_bf16 v[228:243], v[160:163], v[112:115], v[0:15]
	ds_read_b128 v[160:163], v209 offset:0xa010
	s_waitcnt lgkmcnt(3)
	v_mfma_f32_32x32x16_bf16 v[178:193], v[164:167], v[112:115], v[0:15]
	ds_read_b128 v[164:167], v209 offset:0xd010
	s_cmp_ge_i32 s22, s17
	s_cbranch_scc1 .Lp2_nd3
	s_mov_b32 m0, s58
	s_nop 0
	global_load_lds_dwordx4 v176, s[62:63]
.Lp2_nd3:
	s_waitcnt lgkmcnt(3)
	v_mfma_f32_32x32x16_bf16 v[228:243], v[168:171], v[116:119], v[228:243]
	ds_read_b128 v[168:171], v217 offset:0xa010
	v_exp_f32_e32 v96, v96
	v_exp_f32_e32 v97, v97
	s_nop 0
	v_add_f32_e32 v246, v96, v97
	s_waitcnt lgkmcnt(3)
	v_mfma_f32_32x32x16_bf16 v[178:193], v[172:175], v[116:119], v[178:193]
	ds_read_b128 v[172:175], v217 offset:0xd010
	v_cvt_pk_bf16_f32 v96, v96, v97
	v_exp_f32_e32 v98, v98
	v_exp_f32_e32 v99, v99
	s_waitcnt lgkmcnt(3)
	v_mfma_f32_32x32x16_bf16 v[228:243], v[160:163], v[120:123], v[228:243]
	ds_read_b128 v[160:163], v207 offset:0xa090
	v_add_f32_e32 v246, v246, v98
	v_add_f32_e32 v246, v246, v99
	v_cvt_pk_bf16_f32 v97, v98, v99
	v_exp_f32_e32 v100, v100
	s_waitcnt lgkmcnt(3)
	v_mfma_f32_32x32x16_bf16 v[178:193], v[164:167], v[120:123], v[178:193]
	ds_read_b128 v[164:167], v207 offset:0xd090
	v_exp_f32_e32 v101, v101
	v_add_f32_e32 v246, v246, v100
	v_add_f32_e32 v246, v246, v101
	v_cvt_pk_bf16_f32 v98, v100, v101
	s_cmp_ge_i32 s22, s17
	s_cbranch_scc1 .Lp2_nd4
	s_add_i32 m0, s58, 0x2000
	s_nop 0
	global_load_lds_dwordx4 v194, s[62:63]
.Lp2_nd4:
	s_waitcnt lgkmcnt(3)
	v_mfma_f32_32x32x16_bf16 v[228:243], v[168:171], v[124:127], v[228:243]
	ds_read_b128 v[168:171], v208 offset:0xa090
	v_exp_f32_e32 v102, v102
	v_exp_f32_e32 v103, v103
	v_add_f32_e32 v246, v246, v102
	s_waitcnt lgkmcnt(3)
	v_mfma_f32_32x32x16_bf16 v[178:193], v[172:175], v[124:127], v[178:193]
	ds_read_b128 v[172:175], v208 offset:0xd090
	v_add_f32_e32 v246, v246, v103
	v_cvt_pk_bf16_f32 v99, v102, v103
	v_exp_f32_e32 v104, v104
	s_waitcnt lgkmcnt(3)
	v_mfma_f32_32x32x16_bf16 v[228:243], v[160:163], v[128:131], v[228:243]
	ds_read_b128 v[160:163], v209 offset:0xa090
	v_exp_f32_e32 v105, v105
	v_add_f32_e32 v246, v246, v104
	v_add_f32_e32 v246, v246, v105
	v_cvt_pk_bf16_f32 v100, v104, v105
	s_waitcnt lgkmcnt(3)
	v_mfma_f32_32x32x16_bf16 v[178:193], v[164:167], v[128:131], v[178:193]
	ds_read_b128 v[164:167], v209 offset:0xd090
	v_exp_f32_e32 v106, v106
	v_exp_f32_e32 v107, v107
	v_add_f32_e32 v246, v246, v106
	s_cmp_ge_i32 s22, s17
	s_cbranch_scc1 .Lp2_nd5
	s_add_i32 m0, s58, 0x4000
	s_nop 0
	global_load_lds_dwordx4 v196, s[62:63]
.Lp2_nd5:
	s_waitcnt lgkmcnt(3)
	v_mfma_f32_32x32x16_bf16 v[228:243], v[168:171], v[132:135], v[228:243]
	ds_read_b128 v[168:171], v217 offset:0xa090
	v_add_f32_e32 v246, v246, v107
	v_cvt_pk_bf16_f32 v101, v106, v107
	v_exp_f32_e32 v108, v108
	s_waitcnt lgkmcnt(3)
	v_mfma_f32_32x32x16_bf16 v[178:193], v[172:175], v[132:135], v[178:193]
	ds_read_b128 v[172:175], v217 offset:0xd090
	v_exp_f32_e32 v109, v109
	v_add_f32_e32 v246, v246, v108
	v_add_f32_e32 v246, v246, v109
	v_cvt_pk_bf16_f32 v102, v108, v109
	s_waitcnt lgkmcnt(3)
	v_mfma_f32_32x32x16_bf16 v[228:243], v[160:163], v[136:139], v[228:243]
	ds_read_b128 v[160:163], v207 offset:0xa110
	v_exp_f32_e32 v110, v110
	v_exp_f32_e32 v111, v111
	v_add_f32_e32 v246, v246, v110
	s_waitcnt lgkmcnt(3)
	v_mfma_f32_32x32x16_bf16 v[178:193], v[164:167], v[136:139], v[178:193]
	ds_read_b128 v[164:167], v207 offset:0xd110
	v_add_f32_e32 v246, v246, v111
	v_cvt_pk_bf16_f32 v103, v110, v111
	v_exp_f32_e32 v80, v80
	s_cmp_ge_i32 s24, s17
	s_cbranch_scc1 .Lp2_nd6
	s_add_i32 m0, s58, 0x10000
	s_nop 0
	global_load_lds_dwordx4 v198, s[72:73]
.Lp2_nd6:
	s_waitcnt lgkmcnt(3)
	v_mfma_f32_32x32x16_bf16 v[228:243], v[168:171], v[140:143], v[228:243]
	ds_read_b128 v[168:171], v208 offset:0xa110
	v_exp_f32_e32 v81, v81
	v_add_f32_e32 v246, v246, v80
	v_add_f32_e32 v246, v246, v81
	v_cvt_pk_bf16_f32 v80, v80, v81
	s_waitcnt lgkmcnt(3)
	v_mfma_f32_32x32x16_bf16 v[178:193], v[172:175], v[140:143], v[178:193]
	ds_read_b128 v[172:175], v208 offset:0xd110
	v_exp_f32_e32 v82, v82
	v_exp_f32_e32 v83, v83
	v_add_f32_e32 v246, v246, v82
	s_waitcnt lgkmcnt(3)
	v_mfma_f32_32x32x16_bf16 v[228:243], v[160:163], v[144:147], v[228:243]
	ds_read_b128 v[160:163], v209 offset:0xa110
	v_add_f32_e32 v246, v246, v83
	v_cvt_pk_bf16_f32 v81, v82, v83
	v_exp_f32_e32 v84, v84
	s_waitcnt lgkmcnt(3)
	v_mfma_f32_32x32x16_bf16 v[178:193], v[164:167], v[144:147], v[178:193]
	ds_read_b128 v[164:167], v209 offset:0xd110
	v_exp_f32_e32 v85, v85
	v_add_f32_e32 v246, v246, v84
	v_add_f32_e32 v246, v246, v85
	v_cvt_pk_bf16_f32 v82, v84, v85
	s_cmp_ge_i32 s24, s17
	s_cbranch_scc1 .Lp2_nd7
	s_add_i32 m0, s58, 0x12000
	s_nop 0
	global_load_lds_dwordx4 v200, s[72:73]
; __device__ __forceinline__ unsigned cvt_pk_bf16(float lo, float hi) { unsigned r; asm volatile("v_cvt_pk_bf16_f32 %0, %1, %2" : "=v"(r) : "v"(lo), "v"(hi)); return r; }
; __device__ __forceinline__ float fast_exp2(float x) { return __builtin_amdgcn_exp2f(x); }
; #define LGK(n, f) asm volatile("s_waitcnt lgkmcnt(%1)" : "+v"(f) : "n"(n))
; __device__ __forceinline__ void attn_phase(int wv, const bf16_t* Q, const bf16_t* Kf, const bf16_t* Vt, const bf16_t* proj, bf16_t* mixed, LAS unsigned char* lds) { LIDS
;     ...
;                     if (64 * t + 63 > qw0) {
; #pragma unroll
;                         for (int kb = 0; kb < 2; ++kb)
; #pragma unroll
;                             for (int j = 0; j < 16; ++j) { const int key = 64 * t + 32 * kb + 16 * (j >> 3) + 8 * h + (j & 7); if (key > q) s[kb][j] = -1e30f; }
;                     }
;     ...
;                     float ps = 0.f;
; #pragma unroll
;                     for (int kb = 0; kb < 2; ++kb)
; #pragma unroll
;                         for (int j = 0; j < 16; ++j) { s[kb][j] = fast_exp2(s[kb][j] - mrun); ps += s[kb][j]; }
;                     lsum += ps;
; #pragma unroll
;                     for (int c = 0; c < 4; ++c) {
;                         const int kb = c >> 1, sx = c & 1;
;                         u32x4 pw;
; #pragma unroll
;                         for (int j = 0; j < 4; ++j) pw[j] = cvt_pk_bf16(s[kb][8 * sx + 2 * j], s[kb][8 * sx + 2 * j + 1]);
;                         const bf16x8 pf = __builtin_bit_cast(bf16x8, pw);
; #pragma unroll
;                         for (int bb = 0; bb < 4; ++bb) {
;                             const int j = c * 4 + bb;
;                             LGK(j < 13 ? 3 : 15 - j, fr_[j & 3]);
;                             o[bb] = __builtin_amdgcn_mfma_f32_32x32x16_bf16(fr_[j & 3], pf, o[bb], 0, 0, 0);
.Lp2_nd7:
	s_waitcnt lgkmcnt(3)
	v_mfma_f32_32x32x16_bf16 v[228:243], v[168:171], v[148:151], v[228:243]
	ds_read_b128 v[168:171], v217 offset:0xa110
	v_exp_f32_e32 v86, v86
	v_exp_f32_e32 v87, v87
	v_add_f32_e32 v246, v246, v86
	s_waitcnt lgkmcnt(3)
	v_mfma_f32_32x32x16_bf16 v[178:193], v[172:175], v[148:151], v[178:193]
	ds_read_b128 v[172:175], v217 offset:0xd110
	v_add_f32_e32 v246, v246, v87
	v_cvt_pk_bf16_f32 v83, v86, v87
	v_exp_f32_e32 v88, v88
	s_waitcnt lgkmcnt(3)
	v_mfma_f32_32x32x16_bf16 v[228:243], v[160:163], v[152:155], v[228:243]
	ds_read_b128 v[160:163], v218 offset:0x6010
	v_exp_f32_e32 v89, v89
	v_add_f32_e32 v246, v246, v88
	v_add_f32_e32 v246, v246, v89
	v_cvt_pk_bf16_f32 v84, v88, v89
	s_waitcnt lgkmcnt(3)
	v_mfma_f32_32x32x16_bf16 v[178:193], v[164:167], v[152:155], v[178:193]
	ds_read_b128 v[164:167], v218 offset:0x7010
	v_exp_f32_e32 v90, v90
	v_exp_f32_e32 v91, v91
	v_add_f32_e32 v246, v246, v90
	s_waitcnt lgkmcnt(3)
	v_mfma_f32_32x32x16_bf16 v[228:243], v[168:171], v[156:159], v[228:243]
	ds_read_b128 v[168:171], v218 offset:0x8010
	v_add_f32_e32 v246, v246, v91
	v_cvt_pk_bf16_f32 v85, v90, v91
	v_exp_f32_e32 v92, v92
	s_waitcnt lgkmcnt(3)
	v_mfma_f32_32x32x16_bf16 v[178:193], v[172:175], v[156:159], v[178:193]
	ds_read_b128 v[172:175], v218 offset:0x9010
	v_exp_f32_e32 v93, v93
	v_add_f32_e32 v246, v246, v92
	v_add_f32_e32 v246, v246, v93
	v_cvt_pk_bf16_f32 v86, v92, v93
	s_waitcnt lgkmcnt(3)
	v_mfma_f32_32x32x16_bf16 v[48:63], v[160:163], v[96:99], v[48:63]
	ds_read_b128 v[160:163], v219 offset:0x6010
	v_exp_f32_e32 v94, v94
	v_exp_f32_e32 v95, v95
	v_add_f32_e32 v246, v246, v94
	s_waitcnt lgkmcnt(3)
	v_mfma_f32_32x32x16_bf16 v[32:47], v[164:167], v[96:99], v[32:47]
	ds_read_b128 v[164:167], v219 offset:0x7010
	v_add_f32_e32 v246, v246, v95
	v_cvt_pk_bf16_f32 v87, v94, v95
	v_add_f32_e32 v224, v224, v246
	s_waitcnt lgkmcnt(3)
	v_mfma_f32_32x32x16_bf16 v[16:31], v[168:171], v[96:99], v[16:31]
	ds_read_b128 v[168:171], v219 offset:0x8010
	s_waitcnt lgkmcnt(3)
	v_mfma_f32_32x32x16_bf16 v[64:79], v[172:175], v[96:99], v[64:79]
	ds_read_b128 v[172:175], v219 offset:0x9010
	s_cmp_lg_u32 s24, s21
	s_cbranch_scc1 .Lp2_nomask2
	s_lshl_b32 s23, s21, 6
	v_add_u32_e32 v244, s23, v222
	v_sub_u32_e32 v244, v223, v244
	v_cmp_le_i32_e32 vcc, 0, v244
	s_nop 1
	v_cndmask_b32_e32 v228, v215, v228, vcc
	v_cmp_le_i32_e32 vcc, 1, v244
	s_nop 1
	v_cndmask_b32_e32 v229, v215, v229, vcc
	v_cmp_le_i32_e32 vcc, 2, v244
	s_nop 1
	v_cndmask_b32_e32 v230, v215, v230, vcc
	v_cmp_le_i32_e32 vcc, 3, v244
	s_nop 1
	v_cndmask_b32_e32 v231, v215, v231, vcc
	v_cmp_le_i32_e32 vcc, 4, v244
	s_nop 1
	v_cndmask_b32_e32 v232, v215, v232, vcc
	v_cmp_le_i32_e32 vcc, 5, v244
	s_nop 1
	v_cndmask_b32_e32 v233, v215, v233, vcc
	v_cmp_le_i32_e32 vcc, 6, v244
	s_nop 1
	v_cndmask_b32_e32 v234, v215, v234, vcc
	v_cmp_le_i32_e32 vcc, 7, v244
	s_nop 1
	v_cndmask_b32_e32 v235, v215, v235, vcc
	v_cmp_le_i32_e32 vcc, 16, v244
	s_nop 1
	v_cndmask_b32_e32 v236, v215, v236, vcc
	v_cmp_le_i32_e32 vcc, 17, v244
	s_nop 1
	v_cndmask_b32_e32 v237, v215, v237, vcc
	v_cmp_le_i32_e32 vcc, 18, v244
	s_nop 1
	v_cndmask_b32_e32 v238, v215, v238, vcc
	v_cmp_le_i32_e32 vcc, 19, v244
	s_nop 1
	v_cndmask_b32_e32 v239, v215, v239, vcc
	v_cmp_le_i32_e32 vcc, 20, v244
	s_nop 1
	v_cndmask_b32_e32 v240, v215, v240, vcc
	v_cmp_le_i32_e32 vcc, 21, v244
	s_nop 1
	v_cndmask_b32_e32 v241, v215, v241, vcc
	v_cmp_le_i32_e32 vcc, 22, v244
	s_nop 1
	v_cndmask_b32_e32 v242, v215, v242, vcc
	v_cmp_le_i32_e32 vcc, 23, v244
	s_nop 1
	v_cndmask_b32_e32 v243, v215, v243, vcc
	v_cmp_le_i32_e32 vcc, 32, v244
	s_nop 1
	v_cndmask_b32_e32 v178, v215, v178, vcc
	v_cmp_le_i32_e32 vcc, 33, v244
	s_nop 1
	v_cndmask_b32_e32 v179, v215, v179, vcc
	v_cmp_le_i32_e32 vcc, 34, v244
	s_nop 1
	v_cndmask_b32_e32 v180, v215, v180, vcc
	v_cmp_le_i32_e32 vcc, 35, v244
	s_nop 1
	v_cndmask_b32_e32 v181, v215, v181, vcc
	v_cmp_le_i32_e32 vcc, 36, v244
	s_nop 1
	v_cndmask_b32_e32 v182, v215, v182, vcc
	v_cmp_le_i32_e32 vcc, 37, v244
	s_nop 1
	v_cndmask_b32_e32 v183, v215, v183, vcc
	v_cmp_le_i32_e32 vcc, 38, v244
	s_nop 1
	v_cndmask_b32_e32 v184, v215, v184, vcc
	v_cmp_le_i32_e32 vcc, 39, v244
	s_nop 1
	v_cndmask_b32_e32 v185, v215, v185, vcc
	v_cmp_le_i32_e32 vcc, 48, v244
	s_nop 1
	v_cndmask_b32_e32 v186, v215, v186, vcc
	v_cmp_le_i32_e32 vcc, 49, v244
	s_nop 1
	v_cndmask_b32_e32 v187, v215, v187, vcc
	v_cmp_le_i32_e32 vcc, 50, v244
	s_nop 1
	v_cndmask_b32_e32 v188, v215, v188, vcc
	v_cmp_le_i32_e32 vcc, 51, v244
	s_nop 1
	v_cndmask_b32_e32 v189, v215, v189, vcc
	v_cmp_le_i32_e32 vcc, 52, v244
	s_nop 1
	v_cndmask_b32_e32 v190, v215, v190, vcc
	v_cmp_le_i32_e32 vcc, 53, v244
	s_nop 1
	v_cndmask_b32_e32 v191, v215, v191, vcc
	v_cmp_le_i32_e32 vcc, 54, v244
	s_nop 1
	v_cndmask_b32_e32 v192, v215, v192, vcc
	v_cmp_le_i32_e32 vcc, 55, v244
	s_nop 1
	v_cndmask_b32_e32 v193, v215, v193, vcc

; __device__ __forceinline__ float fast_exp2(float x) { return __builtin_amdgcn_exp2f(x); }
; #define LGK(n, f) asm volatile("s_waitcnt lgkmcnt(%1)" : "+v"(f) : "n"(n))
; #define ATT_KRD(i) DSR(fr_[(i) & 3], kad[((i) >> 1) & 3], ((i) & 1) * (32 * 384) + ((i) >> 3) * 128)
; __device__ __forceinline__ void attn_phase(int wv, const bf16_t* Q, const bf16_t* Kf, const bf16_t* Vt, const bf16_t* proj, bf16_t* mixed, LAS unsigned char* lds) { LIDS
;     ...
;                     for (int kb = 0; kb < 2; ++kb)
; #pragma unroll
;                         for (int j = 0; j < 16; ++j) s[kb][j] = zf;
;                     unsigned kad[4];
; #pragma unroll
;                     for (int kl = 0; kl < 4; ++kl) kad[kl] = (unsigned)(size_t)kb_ + (unsigned)koffl[kl];
;                     bf16x8 fr_[4];
;     ...
;                     ATT_KRD(0); ATT_KRD(1); ATT_KRD(2); ATT_KRD(3);
; #pragma unroll
;                     for (int i = 0; i < 24; ++i) {
;                         LGK(i < 21 ? 3 : 23 - i, fr_[i & 3]);
;                         s[i & 1] = __builtin_amdgcn_mfma_f32_32x32x16_bf16(fr_[i & 3], qf[i >> 1], s[i & 1], 0, 0, 0);
;                         if (i + 4 < 24) ATT_KRD(i + 4);
;                     }
;     ...
;                     float ps = 0.f;
; #pragma unroll
;                     for (int kb = 0; kb < 2; ++kb)
; #pragma unroll
;                         for (int j = 0; j < 16; ++j) { s[kb][j] = fast_exp2(s[kb][j] - mrun); ps += s[kb][j]; }
;                     lsum += ps;
.Lp2_top1:
	s_waitcnt lgkmcnt(3)
	v_mfma_f32_32x32x16_bf16 v[96:111], v[160:163], v[112:115], v[0:15]
	ds_read_b128 v[160:163], v209 offset:0x10
	s_waitcnt lgkmcnt(3)
	v_mfma_f32_32x32x16_bf16 v[80:95], v[164:167], v[112:115], v[0:15]
	ds_read_b128 v[164:167], v209 offset:0x3010
	s_cmp_ge_i32 s22, s17
	s_cbranch_scc1 .Lp2_nd9
	s_add_i32 m0, s58, 0xa000
	s_nop 0
	global_load_lds_dwordx4 v176, s[62:63]
.Lp2_nd9:
	s_waitcnt lgkmcnt(3)
	v_mfma_f32_32x32x16_bf16 v[96:111], v[168:171], v[116:119], v[96:111]
	ds_read_b128 v[168:171], v217 offset:0x10
	v_exp_f32_e32 v228, v228
	v_exp_f32_e32 v229, v229
	s_nop 0
	v_add_f32_e32 v246, v228, v229
	s_waitcnt lgkmcnt(3)
	v_mfma_f32_32x32x16_bf16 v[80:95], v[172:175], v[116:119], v[80:95]
	ds_read_b128 v[172:175], v217 offset:0x3010
	v_cvt_pk_bf16_f32 v228, v228, v229
	v_exp_f32_e32 v230, v230
	v_exp_f32_e32 v231, v231
	s_waitcnt lgkmcnt(3)
	v_mfma_f32_32x32x16_bf16 v[96:111], v[160:163], v[120:123], v[96:111]
	ds_read_b128 v[160:163], v207 offset:0x90
	v_add_f32_e32 v246, v246, v230
	v_add_f32_e32 v246, v246, v231
	v_cvt_pk_bf16_f32 v229, v230, v231
	v_exp_f32_e32 v232, v232
	s_waitcnt lgkmcnt(3)
	v_mfma_f32_32x32x16_bf16 v[80:95], v[164:167], v[120:123], v[80:95]
	ds_read_b128 v[164:167], v207 offset:0x3090
	v_exp_f32_e32 v233, v233
	v_add_f32_e32 v246, v246, v232
	v_add_f32_e32 v246, v246, v233
	v_cvt_pk_bf16_f32 v230, v232, v233
	s_cmp_ge_i32 s22, s17
	s_cbranch_scc1 .Lp2_nd10
	s_add_i32 m0, s58, 0xc000
	s_nop 0
	global_load_lds_dwordx4 v194, s[62:63]
.Lp2_nd10:
	s_waitcnt lgkmcnt(3)
	v_mfma_f32_32x32x16_bf16 v[96:111], v[168:171], v[124:127], v[96:111]
	ds_read_b128 v[168:171], v208 offset:0x90
	v_exp_f32_e32 v234, v234
	v_exp_f32_e32 v235, v235
	v_add_f32_e32 v246, v246, v234
	s_waitcnt lgkmcnt(3)
	v_mfma_f32_32x32x16_bf16 v[80:95], v[172:175], v[124:127], v[80:95]
	ds_read_b128 v[172:175], v208 offset:0x3090
	v_add_f32_e32 v246, v246, v235
	v_cvt_pk_bf16_f32 v231, v234, v235
	v_exp_f32_e32 v236, v236
	s_waitcnt lgkmcnt(3)
	v_mfma_f32_32x32x16_bf16 v[96:111], v[160:163], v[128:131], v[96:111]
	ds_read_b128 v[160:163], v209 offset:0x90
	v_exp_f32_e32 v237, v237
	v_add_f32_e32 v246, v246, v236
	v_add_f32_e32 v246, v246, v237
	v_cvt_pk_bf16_f32 v232, v236, v237
	s_waitcnt lgkmcnt(3)
	v_mfma_f32_32x32x16_bf16 v[80:95], v[164:167], v[128:131], v[80:95]
	ds_read_b128 v[164:167], v209 offset:0x3090
	v_exp_f32_e32 v238, v238
	v_exp_f32_e32 v239, v239
	v_add_f32_e32 v246, v246, v238
	s_cmp_ge_i32 s22, s17
	s_cbranch_scc1 .Lp2_nd11
	s_add_i32 m0, s58, 0xe000
	s_nop 0
	global_load_lds_dwordx4 v196, s[62:63]
.Lp2_nd11:
	s_waitcnt lgkmcnt(3)
	v_mfma_f32_32x32x16_bf16 v[96:111], v[168:171], v[132:135], v[96:111]
	ds_read_b128 v[168:171], v217 offset:0x90
	v_add_f32_e32 v246, v246, v239
	v_cvt_pk_bf16_f32 v233, v238, v239
	v_exp_f32_e32 v240, v240
	s_waitcnt lgkmcnt(3)
	v_mfma_f32_32x32x16_bf16 v[80:95], v[172:175], v[132:135], v[80:95]
	ds_read_b128 v[172:175], v217 offset:0x3090
	v_exp_f32_e32 v241, v241
	v_add_f32_e32 v246, v246, v240
	v_add_f32_e32 v246, v246, v241
	v_cvt_pk_bf16_f32 v234, v240, v241
	s_waitcnt lgkmcnt(3)
	v_mfma_f32_32x32x16_bf16 v[96:111], v[160:163], v[136:139], v[96:111]
	ds_read_b128 v[160:163], v207 offset:0x110
	v_exp_f32_e32 v242, v242
	v_exp_f32_e32 v243, v243
	v_add_f32_e32 v246, v246, v242
	s_waitcnt lgkmcnt(3)
	v_mfma_f32_32x32x16_bf16 v[80:95], v[164:167], v[136:139], v[80:95]
	ds_read_b128 v[164:167], v207 offset:0x3110
	v_add_f32_e32 v246, v246, v243
	v_cvt_pk_bf16_f32 v235, v242, v243
	v_exp_f32_e32 v178, v178
	s_cmp_ge_i32 s24, s17
	s_cbranch_scc1 .Lp2_nd12
	s_add_i32 m0, s58, 0x6000
	s_nop 0
	global_load_lds_dwordx4 v198, s[72:73]
.Lp2_nd12:
	s_waitcnt lgkmcnt(3)
	v_mfma_f32_32x32x16_bf16 v[96:111], v[168:171], v[140:143], v[96:111]
	ds_read_b128 v[168:171], v208 offset:0x110
	v_exp_f32_e32 v179, v179
	v_add_f32_e32 v246, v246, v178
	v_add_f32_e32 v246, v246, v179
	v_cvt_pk_bf16_f32 v178, v178, v179
	s_waitcnt lgkmcnt(3)
	v_mfma_f32_32x32x16_bf16 v[80:95], v[172:175], v[140:143], v[80:95]
	ds_read_b128 v[172:175], v208 offset:0x3110
	v_exp_f32_e32 v180, v180
	v_exp_f32_e32 v181, v181
	v_add_f32_e32 v246, v246, v180
	s_waitcnt lgkmcnt(3)
	v_mfma_f32_32x32x16_bf16 v[96:111], v[160:163], v[144:147], v[96:111]
	ds_read_b128 v[160:163], v209 offset:0x110
	v_add_f32_e32 v246, v246, v181
	v_cvt_pk_bf16_f32 v179, v180, v181
	v_exp_f32_e32 v182, v182
	s_waitcnt lgkmcnt(3)
	v_mfma_f32_32x32x16_bf16 v[80:95], v[164:167], v[144:147], v[80:95]
	ds_read_b128 v[164:167], v209 offset:0x3110
	v_exp_f32_e32 v183, v183
	v_add_f32_e32 v246, v246, v182
	v_add_f32_e32 v246, v246, v183
	v_cvt_pk_bf16_f32 v180, v182, v183
	s_cmp_ge_i32 s24, s17
	s_cbranch_scc1 .Lp2_nd13
	s_add_i32 m0, s58, 0x8000
	s_nop 0
	global_load_lds_dwordx4 v200, s[72:73]
; __device__ __forceinline__ unsigned cvt_pk_bf16(float lo, float hi) { unsigned r; asm volatile("v_cvt_pk_bf16_f32 %0, %1, %2" : "=v"(r) : "v"(lo), "v"(hi)); return r; }
; __device__ __forceinline__ float fast_exp2(float x) { return __builtin_amdgcn_exp2f(x); }
; #define LGK(n, f) asm volatile("s_waitcnt lgkmcnt(%1)" : "+v"(f) : "n"(n))
; __device__ __forceinline__ void attn_phase(int wv, const bf16_t* Q, const bf16_t* Kf, const bf16_t* Vt, const bf16_t* proj, bf16_t* mixed, LAS unsigned char* lds) { LIDS
;     ...
;                     if (64 * t + 63 > qw0) {
; #pragma unroll
;                         for (int kb = 0; kb < 2; ++kb)
; #pragma unroll
;                             for (int j = 0; j < 16; ++j) { const int key = 64 * t + 32 * kb + 16 * (j >> 3) + 8 * h + (j & 7); if (key > q) s[kb][j] = -1e30f; }
;                     }
;     ...
;                     float ps = 0.f;
; #pragma unroll
;                     for (int kb = 0; kb < 2; ++kb)
; #pragma unroll
;                         for (int j = 0; j < 16; ++j) { s[kb][j] = fast_exp2(s[kb][j] - mrun); ps += s[kb][j]; }
;                     lsum += ps;
; #pragma unroll
;                     for (int c = 0; c < 4; ++c) {
;                         const int kb = c >> 1, sx = c & 1;
;                         u32x4 pw;
; #pragma unroll
;                         for (int j = 0; j < 4; ++j) pw[j] = cvt_pk_bf16(s[kb][8 * sx + 2 * j], s[kb][8 * sx + 2 * j + 1]);
;                         const bf16x8 pf = __builtin_bit_cast(bf16x8, pw);
; #pragma unroll
;                         for (int bb = 0; bb < 4; ++bb) {
;                             const int j = c * 4 + bb;
;                             LGK(j < 13 ? 3 : 15 - j, fr_[j & 3]);
;                             o[bb] = __builtin_amdgcn_mfma_f32_32x32x16_bf16(fr_[j & 3], pf, o[bb], 0, 0, 0);
.Lp2_nd13:
	s_waitcnt lgkmcnt(3)
	v_mfma_f32_32x32x16_bf16 v[96:111], v[168:171], v[148:151], v[96:111]
	ds_read_b128 v[168:171], v217 offset:0x110
	v_exp_f32_e32 v184, v184
	v_exp_f32_e32 v185, v185
	v_add_f32_e32 v246, v246, v184
	s_waitcnt lgkmcnt(3)
	v_mfma_f32_32x32x16_bf16 v[80:95], v[172:175], v[148:151], v[80:95]
	ds_read_b128 v[172:175], v217 offset:0x3110
	v_add_f32_e32 v246, v246, v185
	v_cvt_pk_bf16_f32 v181, v184, v185
	v_exp_f32_e32 v186, v186
	s_waitcnt lgkmcnt(3)
	v_mfma_f32_32x32x16_bf16 v[96:111], v[160:163], v[152:155], v[96:111]
	ds_read_b128 v[160:163], v210 offset:0x8010
	v_exp_f32_e32 v187, v187
	v_add_f32_e32 v246, v246, v186
	v_add_f32_e32 v246, v246, v187
	v_cvt_pk_bf16_f32 v182, v186, v187
	s_waitcnt lgkmcnt(3)
	v_mfma_f32_32x32x16_bf16 v[80:95], v[164:167], v[152:155], v[80:95]
	ds_read_b128 v[164:167], v210 offset:0x9010
	v_exp_f32_e32 v188, v188
	v_exp_f32_e32 v189, v189
	v_add_f32_e32 v246, v246, v188
	s_waitcnt lgkmcnt(3)
	v_mfma_f32_32x32x16_bf16 v[96:111], v[168:171], v[156:159], v[96:111]
	ds_read_b128 v[168:171], v210 offset:0xa010
	v_add_f32_e32 v246, v246, v189
	v_cvt_pk_bf16_f32 v183, v188, v189
	v_exp_f32_e32 v190, v190
	s_waitcnt lgkmcnt(3)
	v_mfma_f32_32x32x16_bf16 v[80:95], v[172:175], v[156:159], v[80:95]
	ds_read_b128 v[172:175], v210 offset:0xb010
	v_exp_f32_e32 v191, v191
	v_add_f32_e32 v246, v246, v190
	v_add_f32_e32 v246, v246, v191
	v_cvt_pk_bf16_f32 v184, v190, v191
	s_waitcnt lgkmcnt(3)
	v_mfma_f32_32x32x16_bf16 v[48:63], v[160:163], v[228:231], v[48:63]
	ds_read_b128 v[160:163], v211 offset:0x8010
	v_exp_f32_e32 v192, v192
	v_exp_f32_e32 v193, v193
	v_add_f32_e32 v246, v246, v192
	s_waitcnt lgkmcnt(3)
	v_mfma_f32_32x32x16_bf16 v[32:47], v[164:167], v[228:231], v[32:47]
	ds_read_b128 v[164:167], v211 offset:0x9010
	v_add_f32_e32 v246, v246, v193
	v_cvt_pk_bf16_f32 v185, v192, v193
	v_add_f32_e32 v224, v224, v246
	s_waitcnt lgkmcnt(3)
	v_mfma_f32_32x32x16_bf16 v[16:31], v[168:171], v[228:231], v[16:31]
	ds_read_b128 v[168:171], v211 offset:0xa010
	s_waitcnt lgkmcnt(3)
	v_mfma_f32_32x32x16_bf16 v[64:79], v[172:175], v[228:231], v[64:79]
	ds_read_b128 v[172:175], v211 offset:0xb010
	s_cmp_lg_u32 s24, s21
	s_cbranch_scc1 .Lp2_nomask8
	s_lshl_b32 s23, s21, 6
	v_add_u32_e32 v244, s23, v222
	v_sub_u32_e32 v244, v223, v244
	v_cmp_le_i32_e32 vcc, 0, v244
	s_nop 1
	v_cndmask_b32_e32 v96, v215, v96, vcc
	v_cmp_le_i32_e32 vcc, 1, v244
	s_nop 1
	v_cndmask_b32_e32 v97, v215, v97, vcc
	v_cmp_le_i32_e32 vcc, 2, v244
	s_nop 1
	v_cndmask_b32_e32 v98, v215, v98, vcc
	v_cmp_le_i32_e32 vcc, 3, v244
	s_nop 1
	v_cndmask_b32_e32 v99, v215, v99, vcc
	v_cmp_le_i32_e32 vcc, 4, v244
	s_nop 1
	v_cndmask_b32_e32 v100, v215, v100, vcc
	v_cmp_le_i32_e32 vcc, 5, v244
	s_nop 1
	v_cndmask_b32_e32 v101, v215, v101, vcc
	v_cmp_le_i32_e32 vcc, 6, v244
	s_nop 1
	v_cndmask_b32_e32 v102, v215, v102, vcc
	v_cmp_le_i32_e32 vcc, 7, v244
	s_nop 1
	v_cndmask_b32_e32 v103, v215, v103, vcc
	v_cmp_le_i32_e32 vcc, 16, v244
	s_nop 1
	v_cndmask_b32_e32 v104, v215, v104, vcc
	v_cmp_le_i32_e32 vcc, 17, v244
	s_nop 1
	v_cndmask_b32_e32 v105, v215, v105, vcc
	v_cmp_le_i32_e32 vcc, 18, v244
	s_nop 1
	v_cndmask_b32_e32 v106, v215, v106, vcc
	v_cmp_le_i32_e32 vcc, 19, v244
	s_nop 1
	v_cndmask_b32_e32 v107, v215, v107, vcc
	v_cmp_le_i32_e32 vcc, 20, v244
	s_nop 1
	v_cndmask_b32_e32 v108, v215, v108, vcc
	v_cmp_le_i32_e32 vcc, 21, v244
	s_nop 1
	v_cndmask_b32_e32 v109, v215, v109, vcc
	v_cmp_le_i32_e32 vcc, 22, v244
	s_nop 1
	v_cndmask_b32_e32 v110, v215, v110, vcc
	v_cmp_le_i32_e32 vcc, 23, v244
	s_nop 1
	v_cndmask_b32_e32 v111, v215, v111, vcc
	v_cmp_le_i32_e32 vcc, 32, v244
	s_nop 1
	v_cndmask_b32_e32 v80, v215, v80, vcc
	v_cmp_le_i32_e32 vcc, 33, v244
	s_nop 1
	v_cndmask_b32_e32 v81, v215, v81, vcc
	v_cmp_le_i32_e32 vcc, 34, v244
	s_nop 1
	v_cndmask_b32_e32 v82, v215, v82, vcc
	v_cmp_le_i32_e32 vcc, 35, v244
	s_nop 1
	v_cndmask_b32_e32 v83, v215, v83, vcc
	v_cmp_le_i32_e32 vcc, 36, v244
	s_nop 1
	v_cndmask_b32_e32 v84, v215, v84, vcc
	v_cmp_le_i32_e32 vcc, 37, v244
	s_nop 1
	v_cndmask_b32_e32 v85, v215, v85, vcc
	v_cmp_le_i32_e32 vcc, 38, v244
	s_nop 1
	v_cndmask_b32_e32 v86, v215, v86, vcc
	v_cmp_le_i32_e32 vcc, 39, v244
	s_nop 1
	v_cndmask_b32_e32 v87, v215, v87, vcc
	v_cmp_le_i32_e32 vcc, 48, v244
	s_nop 1
	v_cndmask_b32_e32 v88, v215, v88, vcc
	v_cmp_le_i32_e32 vcc, 49, v244
	s_nop 1
	v_cndmask_b32_e32 v89, v215, v89, vcc
	v_cmp_le_i32_e32 vcc, 50, v244
	s_nop 1
	v_cndmask_b32_e32 v90, v215, v90, vcc
	v_cmp_le_i32_e32 vcc, 51, v244
	s_nop 1
	v_cndmask_b32_e32 v91, v215, v91, vcc
	v_cmp_le_i32_e32 vcc, 52, v244
	s_nop 1
	v_cndmask_b32_e32 v92, v215, v92, vcc
	v_cmp_le_i32_e32 vcc, 53, v244
	s_nop 1
	v_cndmask_b32_e32 v93, v215, v93, vcc
	v_cmp_le_i32_e32 vcc, 54, v244
	s_nop 1
	v_cndmask_b32_e32 v94, v215, v94, vcc
	v_cmp_le_i32_e32 vcc, 55, v244
	s_nop 1
	v_cndmask_b32_e32 v95, v215, v95, vcc
